# barrier poll loops: s_sleep 1 replaced by s_sleep 0 (poll cadence tuning)
# baseline (speedup 1.0000x reference)
.LBB0_68:
	s_sleep 0
	global_load_dword v4, v2, s[6:7] offset:32 sc1
	s_waitcnt vmcnt(0)
	v_and_b32_e32 v4, 0xffff0000, v4
	v_cmp_ne_u32_e32 vcc, v4, v3
	s_or_b64 s[8:9], vcc, s[8:9]
	s_andn2_b64 exec, exec, s[8:9]
	s_cbranch_execnz .LBB0_68

.LBB0_75:
	global_load_dword v17, v18, s[8:9] sc1
	s_waitcnt lgkmcnt(0)
	global_load_dword v2, v18, s[10:11] sc1
	global_load_dword v3, v18, s[12:13] sc1
	global_load_dword v4, v18, s[14:15] sc1
	global_load_dword v5, v18, s[16:17] sc1
	global_load_dword v6, v18, s[18:19] sc1
	global_load_dword v7, v18, s[20:21] sc1
	global_load_dword v8, v18, s[22:23] sc1
	global_load_dword v9, v18, s[24:25] sc1
	global_load_dword v10, v18, s[26:27] sc1
	global_load_dword v11, v18, s[28:29] sc1
	global_load_dword v12, v18, s[30:31] sc1
	global_load_dword v13, v18, s[34:35] sc1
	global_load_dword v14, v18, s[36:37] sc1
	global_load_dword v15, v18, s[38:39] sc1
	global_load_dword v16, v18, s[40:41] sc1
	s_mov_b64 s[42:43], -1
	s_mov_b64 s[44:45], -1
	s_waitcnt vmcnt(14)
	v_add_u32_e32 v19, v2, v17
	s_waitcnt vmcnt(13)
	v_add_u32_e32 v19, v19, v3
	s_waitcnt vmcnt(12)
	v_add_u32_e32 v19, v19, v4
	s_waitcnt vmcnt(11)
	v_add_u32_e32 v19, v19, v5
	s_waitcnt vmcnt(10)
	v_add_u32_e32 v19, v19, v6
	s_waitcnt vmcnt(9)
	v_add_u32_e32 v19, v19, v7
	s_waitcnt vmcnt(8)
	v_add_u32_e32 v19, v19, v8
	s_waitcnt vmcnt(7)
	v_add_u32_e32 v19, v19, v9
	s_waitcnt vmcnt(6)
	v_add_u32_e32 v19, v19, v10
	s_waitcnt vmcnt(5)
	v_add_u32_e32 v19, v19, v11
	s_waitcnt vmcnt(4)
	v_add_u32_e32 v19, v19, v12
	s_waitcnt vmcnt(3)
	v_add_u32_e32 v19, v19, v13
	s_waitcnt vmcnt(2)
	v_add_u32_e32 v19, v19, v14
	s_waitcnt vmcnt(1)
	v_add_u32_e32 v19, v19, v15
	s_waitcnt vmcnt(0)
	v_add_u32_e32 v19, v19, v16
	v_cmp_eq_u32_e32 vcc, s3, v19
	s_cbranch_vccnz .LBB0_74
	s_and_b32 s42, s33, 0xff
	s_cmp_eq_u32 s42, 0
	s_mov_b64 s[42:43], -1
	s_mov_b64 s[46:47], -1
	s_sleep 0
	s_cbranch_scc0 .LBB0_79
	global_load_dword v19, v18, s[6:7] sc1
	s_waitcnt vmcnt(0)
	v_cmp_eq_u32_e32 vcc, 0, v19
	s_cbranch_vccnz .LBB0_81
	s_mov_b64 s[46:47], 0

.LBB0_93:
	s_and_b32 s22, s3, 0xff
	s_mov_b64 s[20:21], -1
	s_cmp_lg_u32 s22, 0
	s_mov_b64 s[24:25], -1
	s_sleep 0
	s_cbranch_scc1 .LBB0_96
	global_load_dword v4, v2, s[12:13] sc1
	s_waitcnt vmcnt(0)
	v_cmp_eq_u32_e32 vcc, 0, v4
	s_cbranch_vccnz .LBB0_98
	s_mov_b64 s[24:25], 0
	s_mov_b64 s[22:23], -1

.LBB0_110:
	s_and_b32 s20, s3, 0xff
	s_cmp_lg_u32 s20, 0
	s_mov_b64 s[22:23], -1
	s_sleep 0
	s_cbranch_scc1 .LBB0_113
	global_load_dword v3, v2, s[12:13] sc1
	s_waitcnt vmcnt(0)
	v_cmp_eq_u32_e32 vcc, 0, v3
	s_cbranch_vccnz .LBB0_115
	s_mov_b64 s[22:23], 0
	s_mov_b64 s[20:21], -1

.LBB0_396:
	s_sleep 0
	global_load_dword v4, v2, s[4:5] offset:32 sc1
	s_waitcnt vmcnt(0)
	v_and_b32_e32 v4, 0xffff0000, v4
	v_cmp_ne_u32_e32 vcc, v4, v3
	s_or_b64 s[6:7], vcc, s[6:7]
	s_andn2_b64 exec, exec, s[6:7]
	s_cbranch_execnz .LBB0_396

.LBB0_403:
	global_load_dword v17, v18, s[6:7] sc1
	s_waitcnt lgkmcnt(0)
	global_load_dword v2, v18, s[8:9] sc1
	global_load_dword v3, v18, s[10:11] sc1
	global_load_dword v4, v18, s[12:13] sc1
	global_load_dword v5, v18, s[14:15] sc1
	global_load_dword v6, v18, s[16:17] sc1
	global_load_dword v7, v18, s[18:19] sc1
	global_load_dword v8, v18, s[20:21] sc1
	global_load_dword v9, v18, s[22:23] sc1
	global_load_dword v10, v18, s[24:25] sc1
	global_load_dword v11, v18, s[26:27] sc1
	global_load_dword v12, v18, s[28:29] sc1
	global_load_dword v13, v18, s[30:31] sc1
	global_load_dword v14, v18, s[34:35] sc1
	global_load_dword v15, v18, s[36:37] sc1
	global_load_dword v16, v18, s[38:39] sc1
	s_mov_b64 s[40:41], -1
	s_mov_b64 s[42:43], -1
	s_waitcnt vmcnt(14)
	v_add_u32_e32 v19, v2, v17
	s_waitcnt vmcnt(13)
	v_add_u32_e32 v19, v19, v3
	s_waitcnt vmcnt(12)
	v_add_u32_e32 v19, v19, v4
	s_waitcnt vmcnt(11)
	v_add_u32_e32 v19, v19, v5
	s_waitcnt vmcnt(10)
	v_add_u32_e32 v19, v19, v6
	s_waitcnt vmcnt(9)
	v_add_u32_e32 v19, v19, v7
	s_waitcnt vmcnt(8)
	v_add_u32_e32 v19, v19, v8
	s_waitcnt vmcnt(7)
	v_add_u32_e32 v19, v19, v9
	s_waitcnt vmcnt(6)
	v_add_u32_e32 v19, v19, v10
	s_waitcnt vmcnt(5)
	v_add_u32_e32 v19, v19, v11
	s_waitcnt vmcnt(4)
	v_add_u32_e32 v19, v19, v12
	s_waitcnt vmcnt(3)
	v_add_u32_e32 v19, v19, v13
	s_waitcnt vmcnt(2)
	v_add_u32_e32 v19, v19, v14
	s_waitcnt vmcnt(1)
	v_add_u32_e32 v19, v19, v15
	s_waitcnt vmcnt(0)
	v_add_u32_e32 v19, v19, v16
	v_cmp_eq_u32_e32 vcc, s3, v19
	s_cbranch_vccnz .LBB0_402
	s_and_b32 s40, s33, 0xff
	s_cmp_eq_u32 s40, 0
	s_mov_b64 s[40:41], -1
	s_mov_b64 s[44:45], -1
	s_sleep 0
	s_cbranch_scc0 .LBB0_407
	global_load_dword v19, v18, s[4:5] sc1
	s_waitcnt vmcnt(0)
	v_cmp_eq_u32_e32 vcc, 0, v19
	s_cbranch_vccnz .LBB0_409
	s_mov_b64 s[44:45], 0

.LBB0_421:
	s_and_b32 s20, s3, 0xff
	s_mov_b64 s[18:19], -1
	s_cmp_lg_u32 s20, 0
	s_mov_b64 s[22:23], -1
	s_sleep 0
	s_cbranch_scc1 .LBB0_424
	global_load_dword v4, v2, s[10:11] sc1
	s_waitcnt vmcnt(0)
	v_cmp_eq_u32_e32 vcc, 0, v4
	s_cbranch_vccnz .LBB0_426
	s_mov_b64 s[22:23], 0
	s_mov_b64 s[20:21], -1

.LBB0_438:
	s_and_b32 s18, s3, 0xff
	s_cmp_lg_u32 s18, 0
	s_mov_b64 s[20:21], -1
	s_sleep 0
	s_cbranch_scc1 .LBB0_441
	global_load_dword v3, v2, s[10:11] sc1
	s_waitcnt vmcnt(0)
	v_cmp_eq_u32_e32 vcc, 0, v3
	s_cbranch_vccnz .LBB0_443
	s_mov_b64 s[20:21], 0
	s_mov_b64 s[18:19], -1

.LBB0_567:
	s_sleep 0
	global_load_dword v3, v1, s[6:7] offset:32 sc1
	s_waitcnt vmcnt(0)
	v_and_b32_e32 v3, 0xffff0000, v3
	v_cmp_ne_u32_e32 vcc, v3, v2
	s_or_b64 s[8:9], vcc, s[8:9]
	s_andn2_b64 exec, exec, s[8:9]
	s_cbranch_execnz .LBB0_567

.LBB0_574:
	global_load_dword v16, v17, s[8:9] sc1
	s_waitcnt lgkmcnt(0)
	global_load_dword v1, v17, s[10:11] sc1
	global_load_dword v2, v17, s[12:13] sc1
	global_load_dword v3, v17, s[14:15] sc1
	global_load_dword v4, v17, s[16:17] sc1
	global_load_dword v5, v17, s[18:19] sc1
	global_load_dword v6, v17, s[20:21] sc1
	global_load_dword v7, v17, s[22:23] sc1
	global_load_dword v8, v17, s[24:25] sc1
	global_load_dword v9, v17, s[26:27] sc1
	global_load_dword v10, v17, s[28:29] sc1
	global_load_dword v11, v17, s[30:31] sc1
	global_load_dword v12, v17, s[34:35] sc1
	global_load_dword v13, v17, s[36:37] sc1
	global_load_dword v14, v17, s[38:39] sc1
	global_load_dword v15, v17, s[40:41] sc1
	s_mov_b64 s[42:43], -1
	s_mov_b64 s[44:45], -1
	s_waitcnt vmcnt(14)
	v_add_u32_e32 v18, v1, v16
	s_waitcnt vmcnt(13)
	v_add_u32_e32 v18, v18, v2
	s_waitcnt vmcnt(12)
	v_add_u32_e32 v18, v18, v3
	s_waitcnt vmcnt(11)
	v_add_u32_e32 v18, v18, v4
	s_waitcnt vmcnt(10)
	v_add_u32_e32 v18, v18, v5
	s_waitcnt vmcnt(9)
	v_add_u32_e32 v18, v18, v6
	s_waitcnt vmcnt(8)
	v_add_u32_e32 v18, v18, v7
	s_waitcnt vmcnt(7)
	v_add_u32_e32 v18, v18, v8
	s_waitcnt vmcnt(6)
	v_add_u32_e32 v18, v18, v9
	s_waitcnt vmcnt(5)
	v_add_u32_e32 v18, v18, v10
	s_waitcnt vmcnt(4)
	v_add_u32_e32 v18, v18, v11
	s_waitcnt vmcnt(3)
	v_add_u32_e32 v18, v18, v12
	s_waitcnt vmcnt(2)
	v_add_u32_e32 v18, v18, v13
	s_waitcnt vmcnt(1)
	v_add_u32_e32 v18, v18, v14
	s_waitcnt vmcnt(0)
	v_add_u32_e32 v18, v18, v15
	v_cmp_eq_u32_e32 vcc, s3, v18
	s_cbranch_vccnz .LBB0_573
	s_and_b32 s42, s33, 0xff
	s_cmp_eq_u32 s42, 0
	s_mov_b64 s[42:43], -1
	s_mov_b64 s[46:47], -1
	s_sleep 0
	s_cbranch_scc0 .LBB0_578
	global_load_dword v18, v17, s[6:7] sc1
	s_waitcnt vmcnt(0)
	v_cmp_eq_u32_e32 vcc, 0, v18
	s_cbranch_vccnz .LBB0_580
	s_mov_b64 s[46:47], 0

.LBB0_592:
	s_and_b32 s22, s3, 0xff
	s_mov_b64 s[20:21], -1
	s_cmp_lg_u32 s22, 0
	s_mov_b64 s[24:25], -1
	s_sleep 0
	s_cbranch_scc1 .LBB0_595
	global_load_dword v3, v1, s[12:13] sc1
	s_waitcnt vmcnt(0)
	v_cmp_eq_u32_e32 vcc, 0, v3
	s_cbranch_vccnz .LBB0_597
	s_mov_b64 s[24:25], 0
	s_mov_b64 s[22:23], -1

.LBB0_609:
	s_and_b32 s20, s3, 0xff
	s_cmp_lg_u32 s20, 0
	s_mov_b64 s[22:23], -1
	s_sleep 0
	s_cbranch_scc1 .LBB0_612
	global_load_dword v2, v1, s[12:13] sc1
	s_waitcnt vmcnt(0)
	v_cmp_eq_u32_e32 vcc, 0, v2
	s_cbranch_vccnz .LBB0_614
	s_mov_b64 s[22:23], 0
	s_mov_b64 s[20:21], -1

.LBB0_642:
	s_sleep 0
	global_load_dword v3, v1, s[8:9] offset:32 sc1
	s_waitcnt vmcnt(0)
	v_and_b32_e32 v3, 0xffff0000, v3
	v_cmp_ne_u32_e32 vcc, v3, v2
	s_or_b64 s[10:11], vcc, s[10:11]
	s_andn2_b64 exec, exec, s[10:11]
	s_cbranch_execnz .LBB0_642

.LBB0_649:
	global_load_dword v16, v17, s[10:11] sc1
	s_waitcnt lgkmcnt(0)
	global_load_dword v1, v17, s[12:13] sc1
	global_load_dword v2, v17, s[14:15] sc1
	global_load_dword v3, v17, s[16:17] sc1
	global_load_dword v4, v17, s[18:19] sc1
	global_load_dword v5, v17, s[20:21] sc1
	global_load_dword v6, v17, s[22:23] sc1
	global_load_dword v7, v17, s[24:25] sc1
	global_load_dword v8, v17, s[26:27] sc1
	global_load_dword v9, v17, s[28:29] sc1
	global_load_dword v10, v17, s[30:31] sc1
	global_load_dword v11, v17, s[34:35] sc1
	global_load_dword v12, v17, s[36:37] sc1
	global_load_dword v13, v17, s[38:39] sc1
	global_load_dword v14, v17, s[40:41] sc1
	global_load_dword v15, v17, s[42:43] sc1
	s_mov_b64 s[44:45], -1
	s_mov_b64 s[46:47], -1
	s_waitcnt vmcnt(14)
	v_add_u32_e32 v18, v1, v16
	s_waitcnt vmcnt(13)
	v_add_u32_e32 v18, v18, v2
	s_waitcnt vmcnt(12)
	v_add_u32_e32 v18, v18, v3
	s_waitcnt vmcnt(11)
	v_add_u32_e32 v18, v18, v4
	s_waitcnt vmcnt(10)
	v_add_u32_e32 v18, v18, v5
	s_waitcnt vmcnt(9)
	v_add_u32_e32 v18, v18, v6
	s_waitcnt vmcnt(8)
	v_add_u32_e32 v18, v18, v7
	s_waitcnt vmcnt(7)
	v_add_u32_e32 v18, v18, v8
	s_waitcnt vmcnt(6)
	v_add_u32_e32 v18, v18, v9
	s_waitcnt vmcnt(5)
	v_add_u32_e32 v18, v18, v10
	s_waitcnt vmcnt(4)
	v_add_u32_e32 v18, v18, v11
	s_waitcnt vmcnt(3)
	v_add_u32_e32 v18, v18, v12
	s_waitcnt vmcnt(2)
	v_add_u32_e32 v18, v18, v13
	s_waitcnt vmcnt(1)
	v_add_u32_e32 v18, v18, v14
	s_waitcnt vmcnt(0)
	v_add_u32_e32 v18, v18, v15
	v_cmp_eq_u32_e32 vcc, s3, v18
	s_cbranch_vccnz .LBB0_648
	s_and_b32 s44, s33, 0xff
	s_cmp_eq_u32 s44, 0
	s_mov_b64 s[44:45], -1
	s_mov_b64 s[48:49], -1
	s_sleep 0
	s_cbranch_scc0 .LBB0_653
	global_load_dword v18, v17, s[8:9] sc1
	s_waitcnt vmcnt(0)
	v_cmp_eq_u32_e32 vcc, 0, v18
	s_cbranch_vccnz .LBB0_655
	s_mov_b64 s[48:49], 0

.LBB0_667:
	s_and_b32 s24, s3, 0xff
	s_mov_b64 s[22:23], -1
	s_cmp_lg_u32 s24, 0
	s_mov_b64 s[26:27], -1
	s_sleep 0
	s_cbranch_scc1 .LBB0_670
	global_load_dword v3, v1, s[14:15] sc1
	s_waitcnt vmcnt(0)
	v_cmp_eq_u32_e32 vcc, 0, v3
	s_cbranch_vccnz .LBB0_672
	s_mov_b64 s[26:27], 0
	s_mov_b64 s[24:25], -1

.LBB0_684:
	s_and_b32 s22, s3, 0xff
	s_cmp_lg_u32 s22, 0
	s_mov_b64 s[24:25], -1
	s_sleep 0
	s_cbranch_scc1 .LBB0_687
	global_load_dword v2, v1, s[14:15] sc1
	s_waitcnt vmcnt(0)
	v_cmp_eq_u32_e32 vcc, 0, v2
	s_cbranch_vccnz .LBB0_689
	s_mov_b64 s[24:25], 0
	s_mov_b64 s[22:23], -1

.LBB0_821:
	s_sleep 0
	global_load_dword v2, v0, s[8:9] offset:32 sc1
	s_waitcnt vmcnt(0)
	v_and_b32_e32 v2, 0xffff0000, v2
	v_cmp_ne_u32_e32 vcc, v2, v1
	s_or_b64 s[10:11], vcc, s[10:11]
	s_andn2_b64 exec, exec, s[10:11]
	s_cbranch_execnz .LBB0_821

.LBB0_828:
	global_load_dword v15, v16, s[10:11] sc1
	s_waitcnt lgkmcnt(0)
	global_load_dword v0, v16, s[12:13] sc1
	global_load_dword v1, v16, s[14:15] sc1
	global_load_dword v2, v16, s[16:17] sc1
	global_load_dword v3, v16, s[18:19] sc1
	global_load_dword v4, v16, s[20:21] sc1
	global_load_dword v5, v16, s[22:23] sc1
	global_load_dword v6, v16, s[24:25] sc1
	global_load_dword v7, v16, s[26:27] sc1
	global_load_dword v8, v16, s[28:29] sc1
	global_load_dword v9, v16, s[30:31] sc1
	global_load_dword v10, v16, s[34:35] sc1
	global_load_dword v11, v16, s[36:37] sc1
	global_load_dword v12, v16, s[38:39] sc1
	global_load_dword v13, v16, s[40:41] sc1
	global_load_dword v14, v16, s[42:43] sc1
	s_mov_b64 s[44:45], -1
	s_mov_b64 s[46:47], -1
	s_waitcnt vmcnt(14)
	v_add_u32_e32 v17, v0, v15
	s_waitcnt vmcnt(13)
	v_add_u32_e32 v17, v17, v1
	s_waitcnt vmcnt(12)
	v_add_u32_e32 v17, v17, v2
	s_waitcnt vmcnt(11)
	v_add_u32_e32 v17, v17, v3
	s_waitcnt vmcnt(10)
	v_add_u32_e32 v17, v17, v4
	s_waitcnt vmcnt(9)
	v_add_u32_e32 v17, v17, v5
	s_waitcnt vmcnt(8)
	v_add_u32_e32 v17, v17, v6
	s_waitcnt vmcnt(7)
	v_add_u32_e32 v17, v17, v7
	s_waitcnt vmcnt(6)
	v_add_u32_e32 v17, v17, v8
	s_waitcnt vmcnt(5)
	v_add_u32_e32 v17, v17, v9
	s_waitcnt vmcnt(4)
	v_add_u32_e32 v17, v17, v10
	s_waitcnt vmcnt(3)
	v_add_u32_e32 v17, v17, v11
	s_waitcnt vmcnt(2)
	v_add_u32_e32 v17, v17, v12
	s_waitcnt vmcnt(1)
	v_add_u32_e32 v17, v17, v13
	s_waitcnt vmcnt(0)
	v_add_u32_e32 v17, v17, v14
	v_cmp_eq_u32_e32 vcc, s3, v17
	s_cbranch_vccnz .LBB0_827
	s_and_b32 s44, s33, 0xff
	s_cmp_eq_u32 s44, 0
	s_mov_b64 s[44:45], -1
	s_mov_b64 s[48:49], -1
	s_sleep 0
	s_cbranch_scc0 .LBB0_832
	global_load_dword v17, v16, s[8:9] sc1
	s_waitcnt vmcnt(0)
	v_cmp_eq_u32_e32 vcc, 0, v17
	s_cbranch_vccnz .LBB0_834
	s_mov_b64 s[48:49], 0

.LBB0_846:
	s_and_b32 s24, s3, 0xff
	s_mov_b64 s[22:23], -1
	s_cmp_lg_u32 s24, 0
	s_mov_b64 s[26:27], -1
	s_sleep 0
	s_cbranch_scc1 .LBB0_849
	global_load_dword v2, v0, s[14:15] sc1
	s_waitcnt vmcnt(0)
	v_cmp_eq_u32_e32 vcc, 0, v2
	s_cbranch_vccnz .LBB0_851
	s_mov_b64 s[26:27], 0
	s_mov_b64 s[24:25], -1

.LBB0_863:
	s_and_b32 s22, s3, 0xff
	s_cmp_lg_u32 s22, 0
	s_mov_b64 s[24:25], -1
	s_sleep 0
	s_cbranch_scc1 .LBB0_866
	global_load_dword v1, v0, s[14:15] sc1
	s_waitcnt vmcnt(0)
	v_cmp_eq_u32_e32 vcc, 0, v1
	s_cbranch_vccnz .LBB0_868
	s_mov_b64 s[24:25], 0
	s_mov_b64 s[22:23], -1
